# shiftw wave_sum: xor 1/2/4/8 steps as v_add_f32_dpp, xor 16/32 as v_permlane16/32_swap, instead of 30 serialized ds_bpermute per row; on top of v51
# baseline (speedup 1.0000x reference)
; #define LAS __attribute__((address_space(3)))
; __device__ __forceinline__ void unpack8(const u32x4 w, float (&f)[8]) { f[0] = bflo(w.x); f[1] = bfhi(w.x); f[2] = bflo(w.y); f[3] = bfhi(w.y); f[4] = bflo(w.z); f[5] = bfhi(w.z); f[6] = bflo(w.w); f[7] = bfhi(w.w); }
; __device__ __forceinline__ float wave_sum(float v) {
; #pragma unroll
;     for (int o = 1; o < 64; o <<= 1) v += __shfl_xor(v, o);
;     return v;
; }
; __device__ __forceinline__ void shiftw_phase(const Args& a, int layer, LAS unsigned char* lds, int tid, int gw, int ngw, int lane) {
;     ...
;         for (int n = gw; n < N; n += ngw) {
;             const bf16_t* wr_ = Wt + (size_t)n * DM + lane * 8;
;             float w[4][8];
; #pragma unroll
;             for (int j = 0; j < 4; ++j) unpack8(*(const u32x4*)(wr_ + 512 * j), w[j]);
;             float accv[5];
; #pragma unroll
;             for (int v = 0; v < 5; ++v) { float s_ = 0.f;
; #pragma unroll
;                 for (int j = 0; j < 4; ++j) { const LAS f32x4* sp = (const LAS f32x4*)(sh + v * DM + lane * 8 + 512 * j); const f32x4 s0 = sp[0], s1 = sp[1];
;                     s_ += (w[j][0] * s0[0] + w[j][1] * s0[1]) + (w[j][2] * s0[2] + w[j][3] * s0[3]) + (w[j][4] * s1[0] + w[j][5] * s1[1]) + (w[j][6] * s1[2] + w[j][7] * s1[3]); }
;                 accv[v] = wave_sum(s_); }
;             if (lane < 5) { float r = accv[0]; r = lane == 1 ? accv[1] : r; r = lane == 2 ? accv[2] : r; r = lane == 3 ? accv[3] : r; r = lane == 4 ? accv[4] : r;
;                 SW[((size_t)kind * 5 + lane) * SWLD + n] = r; }
.LBB0_146:
	global_load_dwordx4 v[198:201], v[172:173], off offset:-2048
	global_load_dwordx4 v[206:209], v[172:173], off offset:-1024
	global_load_dwordx4 v[214:217], v[172:173], off
	global_load_dwordx4 v[222:225], v[172:173], off offset:1024
	s_waitcnt vmcnt(3)
	v_and_b32_e32 v197, 0xffff0000, v198
	v_and_b32_e32 v196, 0xffff0000, v199
	v_lshlrev_b32_e32 v194, 16, v198
	v_lshlrev_b32_e32 v193, 16, v199
	s_waitcnt lgkmcnt(0)
	v_mul_f32_e32 v180, v3, v197
	v_mul_f32_e32 v181, v5, v196
	v_and_b32_e32 v195, 0xffff0000, v200
	v_fmac_f32_e32 v180, v2, v194
	v_fmac_f32_e32 v181, v4, v193
	s_waitcnt lgkmcnt(0)
	v_lshlrev_b32_e32 v191, 16, v200
	v_add_f32_e32 v180, v180, v181
	v_mul_f32_e32 v181, v7, v195
	v_and_b32_e32 v192, 0xffff0000, v201
	v_fmac_f32_e32 v181, v6, v191
	v_lshlrev_b32_e32 v190, 16, v201
	v_add_f32_e32 v180, v180, v181
	v_mul_f32_e32 v181, v9, v192
	s_waitcnt vmcnt(2)
	v_and_b32_e32 v205, 0xffff0000, v206
	v_and_b32_e32 v204, 0xffff0000, v207
	v_fmac_f32_e32 v181, v8, v190
	v_lshlrev_b32_e32 v202, 16, v206
	v_lshlrev_b32_e32 v201, 16, v207
	s_waitcnt vmcnt(0)
	v_lshlrev_b32_e32 v218, 16, v222
	v_and_b32_e32 v221, 0xffff0000, v222
	v_add_f32_e32 v180, v181, v180
	v_mul_f32_e32 v181, v11, v205
	v_mul_f32_e32 v222, v13, v204
	v_and_b32_e32 v203, 0xffff0000, v208
	v_fmac_f32_e32 v181, v10, v202
	v_fmac_f32_e32 v222, v12, v201
	v_lshlrev_b32_e32 v199, 16, v208
	v_add_f32_e32 v181, v181, v222
	v_mul_f32_e32 v222, v15, v203
	v_and_b32_e32 v200, 0xffff0000, v209
	v_fmac_f32_e32 v222, v14, v199
	v_lshlrev_b32_e32 v198, 16, v209
	v_add_f32_e32 v181, v181, v222
	v_mul_f32_e32 v222, v17, v200
	v_fmac_f32_e32 v222, v16, v198
	v_and_b32_e32 v213, 0xffff0000, v214
	v_and_b32_e32 v212, 0xffff0000, v215
	v_add_f32_e32 v180, 0, v180
	v_add_f32_e32 v181, v222, v181
	v_lshlrev_b32_e32 v210, 16, v214
	v_lshlrev_b32_e32 v209, 16, v215
	v_add_f32_e32 v180, v180, v181
	v_mul_f32_e32 v181, v19, v213
	v_mul_f32_e32 v222, v21, v212
	v_and_b32_e32 v211, 0xffff0000, v216
	v_fmac_f32_e32 v181, v18, v210
	v_fmac_f32_e32 v222, v20, v209
	v_lshlrev_b32_e32 v207, 16, v216
	v_add_f32_e32 v181, v181, v222
	v_mul_f32_e32 v222, v23, v211
	v_and_b32_e32 v208, 0xffff0000, v217
	v_fmac_f32_e32 v222, v22, v207
	v_lshlrev_b32_e32 v206, 16, v217
	v_add_f32_e32 v181, v181, v222
	v_mul_f32_e32 v222, v25, v208
	v_fmac_f32_e32 v222, v24, v206
	v_and_b32_e32 v220, 0xffff0000, v223
	v_add_f32_e32 v181, v222, v181
	v_lshlrev_b32_e32 v217, 16, v223
	v_add_f32_e32 v180, v180, v181
	v_mul_f32_e32 v181, v27, v221
	v_mul_f32_e32 v222, v29, v220
	v_and_b32_e32 v219, 0xffff0000, v224
	v_fmac_f32_e32 v181, v26, v218
	v_fmac_f32_e32 v222, v28, v217
	v_lshlrev_b32_e32 v215, 16, v224
	v_add_f32_e32 v181, v181, v222
	v_mul_f32_e32 v222, v31, v219
	v_and_b32_e32 v216, 0xffff0000, v225
	v_fmac_f32_e32 v222, v30, v215
	v_lshlrev_b32_e32 v214, 16, v225
	v_add_f32_e32 v181, v181, v222
	v_mul_f32_e32 v222, v33, v216
	v_fmac_f32_e32 v222, v32, v214
	v_add_f32_e32 v181, v222, v181
	v_add_f32_e32 v180, v180, v181
	v_mul_f32_e32 v224, v45, v204
	v_fmac_f32_e32 v224, v44, v201
	v_mul_f32_e32 v226, v77, v204
	v_fmac_f32_e32 v226, v76, v201
	s_waitcnt lgkmcnt(0)
	s_nop 1
	v_add_f32_dpp v180, v180, v180 quad_perm:[1,0,3,2] row_mask:0xf bank_mask:0xf
	v_mul_f32_e32 v228, v109, v204
	v_fmac_f32_e32 v228, v108, v201
	s_waitcnt lgkmcnt(0)
	s_nop 1
	v_add_f32_dpp v180, v180, v180 quad_perm:[2,3,0,1] row_mask:0xf bank_mask:0xf
	s_waitcnt lgkmcnt(0)
	s_nop 1
	v_add_f32_dpp v180, v180, v180 row_half_mirror row_mask:0xf bank_mask:0xf
	s_waitcnt lgkmcnt(0)
	s_nop 1
	v_add_f32_dpp v180, v180, v180 row_mirror row_mask:0xf bank_mask:0xf
	v_mov_b32_e32 v181, v180
	s_nop 1
	v_permlane16_swap_b32 v180, v181
	s_waitcnt lgkmcnt(0)
	v_add_f32_e32 v222, v180, v181
	v_mul_f32_e32 v180, v35, v197
	v_mul_f32_e32 v181, v37, v196
	v_fmac_f32_e32 v180, v34, v194
	v_fmac_f32_e32 v181, v36, v193
	v_add_f32_e32 v180, v180, v181
	v_mul_f32_e32 v181, v39, v195
	v_fmac_f32_e32 v181, v38, v191
	v_add_f32_e32 v180, v180, v181
	v_mul_f32_e32 v181, v41, v192
	v_fmac_f32_e32 v181, v40, v190
	v_add_f32_e32 v180, v181, v180
	v_mul_f32_e32 v181, v43, v205
	v_fmac_f32_e32 v181, v42, v202
	v_add_f32_e32 v181, v181, v224
	v_mul_f32_e32 v224, v47, v203
	v_fmac_f32_e32 v224, v46, v199
	v_add_f32_e32 v181, v181, v224
	v_mul_f32_e32 v224, v49, v200
	v_fmac_f32_e32 v224, v48, v198
	v_add_f32_e32 v180, 0, v180
	v_add_f32_e32 v181, v224, v181
	v_add_f32_e32 v180, v180, v181
	v_mul_f32_e32 v181, v51, v213
	v_mul_f32_e32 v224, v53, v212
	v_fmac_f32_e32 v181, v50, v210
	v_fmac_f32_e32 v224, v52, v209
	v_add_f32_e32 v181, v181, v224
	v_mul_f32_e32 v224, v55, v211
	v_fmac_f32_e32 v224, v54, v207
	v_add_f32_e32 v181, v181, v224
	v_mul_f32_e32 v224, v57, v208
	v_fmac_f32_e32 v224, v56, v206
	v_add_f32_e32 v181, v224, v181
	v_add_f32_e32 v180, v180, v181
	v_mul_f32_e32 v181, v59, v221
	v_mul_f32_e32 v224, v61, v220
	v_fmac_f32_e32 v181, v58, v218
	v_fmac_f32_e32 v224, v60, v217
	v_add_f32_e32 v181, v181, v224
	v_mul_f32_e32 v224, v63, v219
	v_fmac_f32_e32 v224, v62, v215
	v_add_f32_e32 v181, v181, v224
	v_mul_f32_e32 v224, v65, v216
	v_fmac_f32_e32 v224, v64, v214
	v_add_f32_e32 v181, v224, v181
	v_add_f32_e32 v180, v180, v181
	v_mov_b32_e32 v223, v222
	s_nop 1
	v_permlane32_swap_b32 v222, v223
	s_waitcnt lgkmcnt(0)
	s_nop 1
	v_add_f32_dpp v180, v180, v180 quad_perm:[1,0,3,2] row_mask:0xf bank_mask:0xf
	s_waitcnt lgkmcnt(0)
	s_nop 1
	v_add_f32_dpp v180, v180, v180 quad_perm:[2,3,0,1] row_mask:0xf bank_mask:0xf
	s_waitcnt lgkmcnt(0)
	s_nop 1
	v_add_f32_dpp v180, v180, v180 row_half_mirror row_mask:0xf bank_mask:0xf
	s_waitcnt lgkmcnt(0)
; #define LAS __attribute__((address_space(3)))
; __device__ __forceinline__ void unpack8(const u32x4 w, float (&f)[8]) { f[0] = bflo(w.x); f[1] = bfhi(w.x); f[2] = bflo(w.y); f[3] = bfhi(w.y); f[4] = bflo(w.z); f[5] = bfhi(w.z); f[6] = bflo(w.w); f[7] = bfhi(w.w); }
; __device__ __forceinline__ float wave_sum(float v) {
; #pragma unroll
;     for (int o = 1; o < 64; o <<= 1) v += __shfl_xor(v, o);
;     return v;
; }
; __device__ __forceinline__ void shiftw_phase(const Args& a, int layer, LAS unsigned char* lds, int tid, int gw, int ngw, int lane) {
;     ...
;         for (int n = gw; n < N; n += ngw) {
;             const bf16_t* wr_ = Wt + (size_t)n * DM + lane * 8;
;             float w[4][8];
; #pragma unroll
;             for (int j = 0; j < 4; ++j) unpack8(*(const u32x4*)(wr_ + 512 * j), w[j]);
;             float accv[5];
; #pragma unroll
;             for (int v = 0; v < 5; ++v) { float s_ = 0.f;
; #pragma unroll
;                 for (int j = 0; j < 4; ++j) { const LAS f32x4* sp = (const LAS f32x4*)(sh + v * DM + lane * 8 + 512 * j); const f32x4 s0 = sp[0], s1 = sp[1];
;                     s_ += (w[j][0] * s0[0] + w[j][1] * s0[1]) + (w[j][2] * s0[2] + w[j][3] * s0[3]) + (w[j][4] * s1[0] + w[j][5] * s1[1]) + (w[j][6] * s1[2] + w[j][7] * s1[3]); }
;                 accv[v] = wave_sum(s_); }
;             if (lane < 5) { float r = accv[0]; r = lane == 1 ? accv[1] : r; r = lane == 2 ? accv[2] : r; r = lane == 3 ? accv[3] : r; r = lane == 4 ? accv[4] : r;
;                 SW[((size_t)kind * 5 + lane) * SWLD + n] = r; }
	s_nop 1
	v_add_f32_dpp v180, v180, v180 row_mirror row_mask:0xf bank_mask:0xf
	v_mov_b32_e32 v181, v180
	s_nop 1
	v_permlane16_swap_b32 v180, v181
	s_waitcnt lgkmcnt(0)
	v_add_f32_e32 v224, v180, v181
	v_mul_f32_e32 v180, v67, v197
	v_mul_f32_e32 v181, v69, v196
	v_fmac_f32_e32 v180, v66, v194
	v_fmac_f32_e32 v181, v68, v193
	v_add_f32_e32 v180, v180, v181
	v_mul_f32_e32 v181, v71, v195
	v_fmac_f32_e32 v181, v70, v191
	v_add_f32_e32 v180, v180, v181
	v_mul_f32_e32 v181, v73, v192
	v_fmac_f32_e32 v181, v72, v190
	v_add_f32_e32 v180, v181, v180
	v_mul_f32_e32 v181, v75, v205
	v_fmac_f32_e32 v181, v74, v202
	v_add_f32_e32 v181, v181, v226
	v_mul_f32_e32 v226, v79, v203
	v_fmac_f32_e32 v226, v78, v199
	v_add_f32_e32 v181, v181, v226
	v_mul_f32_e32 v226, v81, v200
	v_fmac_f32_e32 v226, v80, v198
	v_add_f32_e32 v180, 0, v180
	v_add_f32_e32 v181, v226, v181
	v_add_f32_e32 v180, v180, v181
	v_mul_f32_e32 v181, v83, v213
	v_mul_f32_e32 v226, v85, v212
	v_fmac_f32_e32 v181, v82, v210
	v_fmac_f32_e32 v226, v84, v209
	v_add_f32_e32 v181, v181, v226
	v_mul_f32_e32 v226, v87, v211
	v_fmac_f32_e32 v226, v86, v207
	v_add_f32_e32 v181, v181, v226
	v_mul_f32_e32 v226, v89, v208
	v_fmac_f32_e32 v226, v88, v206
	v_add_f32_e32 v181, v226, v181
	v_add_f32_e32 v180, v180, v181
	v_mul_f32_e32 v181, v91, v221
	v_mul_f32_e32 v226, v93, v220
	v_fmac_f32_e32 v181, v90, v218
	v_fmac_f32_e32 v226, v92, v217
	v_add_f32_e32 v181, v181, v226
	v_mul_f32_e32 v226, v95, v219
	v_fmac_f32_e32 v226, v94, v215
	v_add_f32_e32 v181, v181, v226
	v_mul_f32_e32 v226, v97, v216
	v_fmac_f32_e32 v226, v96, v214
	v_add_f32_e32 v181, v226, v181
	v_add_f32_e32 v180, v180, v181
	v_mov_b32_e32 v225, v224
	s_nop 1
	v_permlane32_swap_b32 v224, v225
	s_waitcnt lgkmcnt(0)
	s_nop 1
	v_add_f32_dpp v180, v180, v180 quad_perm:[1,0,3,2] row_mask:0xf bank_mask:0xf
	s_waitcnt lgkmcnt(0)
	s_nop 1
	v_add_f32_dpp v180, v180, v180 quad_perm:[2,3,0,1] row_mask:0xf bank_mask:0xf
	s_waitcnt lgkmcnt(0)
	s_nop 1
	v_add_f32_dpp v180, v180, v180 row_half_mirror row_mask:0xf bank_mask:0xf
	s_waitcnt lgkmcnt(0)
	s_nop 1
	v_add_f32_dpp v180, v180, v180 row_mirror row_mask:0xf bank_mask:0xf
	v_mov_b32_e32 v181, v180
	s_nop 1
	v_permlane16_swap_b32 v180, v181
	s_waitcnt lgkmcnt(0)
	v_add_f32_e32 v226, v180, v181
	v_mul_f32_e32 v180, v99, v197
	v_mul_f32_e32 v181, v101, v196
	v_fmac_f32_e32 v180, v98, v194
	v_fmac_f32_e32 v181, v100, v193
	v_add_f32_e32 v180, v180, v181
	v_mul_f32_e32 v181, v103, v195
	v_fmac_f32_e32 v181, v102, v191
	v_add_f32_e32 v180, v180, v181
	v_mul_f32_e32 v181, v105, v192
	v_fmac_f32_e32 v181, v104, v190
	v_add_f32_e32 v180, v181, v180
	v_mul_f32_e32 v181, v107, v205
	v_fmac_f32_e32 v181, v106, v202
	v_add_f32_e32 v181, v181, v228
	v_mul_f32_e32 v228, v111, v203
	v_fmac_f32_e32 v228, v110, v199
	v_add_f32_e32 v181, v181, v228
	v_mul_f32_e32 v228, v113, v200
	v_fmac_f32_e32 v228, v112, v198
	v_add_f32_e32 v180, 0, v180
	v_add_f32_e32 v181, v228, v181
	v_add_f32_e32 v180, v180, v181
	v_mul_f32_e32 v181, v115, v213
	v_mul_f32_e32 v228, v117, v212
	v_fmac_f32_e32 v181, v114, v210
	v_fmac_f32_e32 v228, v116, v209
	v_add_f32_e32 v181, v181, v228
	v_mul_f32_e32 v228, v119, v211
	v_fmac_f32_e32 v228, v118, v207
	v_add_f32_e32 v181, v181, v228
	v_mul_f32_e32 v228, v121, v208
	v_fmac_f32_e32 v228, v120, v206
	v_add_f32_e32 v181, v228, v181
	v_add_f32_e32 v180, v180, v181
	v_mul_f32_e32 v181, v123, v221
	v_mul_f32_e32 v228, v125, v220
	v_fmac_f32_e32 v181, v122, v218
	v_fmac_f32_e32 v228, v124, v217
	v_add_f32_e32 v181, v181, v228
	v_mul_f32_e32 v228, v127, v219
	v_fmac_f32_e32 v228, v126, v215
	v_add_f32_e32 v181, v181, v228
	v_mul_f32_e32 v228, v129, v216
	v_fmac_f32_e32 v228, v128, v214
	v_add_f32_e32 v181, v228, v181
	v_add_f32_e32 v180, v180, v181
	v_mov_b32_e32 v227, v226
	s_nop 1
	v_permlane32_swap_b32 v226, v227
	s_waitcnt lgkmcnt(0)
	s_nop 1
	v_add_f32_dpp v180, v180, v180 quad_perm:[1,0,3,2] row_mask:0xf bank_mask:0xf
	s_waitcnt lgkmcnt(0)
	s_nop 1
	v_add_f32_dpp v180, v180, v180 quad_perm:[2,3,0,1] row_mask:0xf bank_mask:0xf
	s_waitcnt lgkmcnt(0)
	s_nop 1
	v_add_f32_dpp v180, v180, v180 row_half_mirror row_mask:0xf bank_mask:0xf
	s_waitcnt lgkmcnt(0)
	s_nop 1
	v_add_f32_dpp v180, v180, v180 row_mirror row_mask:0xf bank_mask:0xf
	v_mov_b32_e32 v181, v180
	s_nop 1
	v_permlane16_swap_b32 v180, v181
	s_waitcnt lgkmcnt(0)
	v_add_f32_e32 v228, v180, v181
	v_mul_f32_e32 v180, v131, v197
	v_mul_f32_e32 v181, v133, v196
	v_fmac_f32_e32 v180, v130, v194
	v_fmac_f32_e32 v181, v132, v193
	v_add_f32_e32 v180, v180, v181
	v_mul_f32_e32 v181, v135, v195
	v_fmac_f32_e32 v181, v134, v191
	v_add_f32_e32 v180, v180, v181
	v_mul_f32_e32 v181, v137, v192
	v_fmac_f32_e32 v181, v136, v190
	v_add_f32_e32 v180, v181, v180
	v_mul_f32_e32 v181, v139, v205
	v_mul_f32_e32 v190, v141, v204
	v_fmac_f32_e32 v181, v138, v202
	v_fmac_f32_e32 v190, v140, v201
	v_add_f32_e32 v181, v181, v190
	v_mul_f32_e32 v190, v143, v203
	v_fmac_f32_e32 v190, v142, v199
	v_add_f32_e32 v181, v181, v190
	v_mul_f32_e32 v190, v145, v200
	v_fmac_f32_e32 v190, v144, v198
	v_add_f32_e32 v180, 0, v180
	v_add_f32_e32 v181, v190, v181
	v_add_f32_e32 v180, v180, v181
	v_mul_f32_e32 v181, v147, v213
	v_mul_f32_e32 v190, v149, v212
	v_fmac_f32_e32 v181, v146, v210
	v_fmac_f32_e32 v190, v148, v209
	v_add_f32_e32 v181, v181, v190
	v_mul_f32_e32 v190, v151, v211
	v_fmac_f32_e32 v190, v150, v207
	v_add_f32_e32 v181, v181, v190
	v_mul_f32_e32 v190, v153, v208
	v_fmac_f32_e32 v190, v152, v206
	v_add_f32_e32 v181, v190, v181
	v_add_f32_e32 v180, v180, v181
	v_mul_f32_e32 v181, v155, v221
	v_mul_f32_e32 v190, v157, v220
	v_fmac_f32_e32 v181, v154, v218
	v_fmac_f32_e32 v190, v156, v217
	v_add_f32_e32 v181, v181, v190
	v_mul_f32_e32 v190, v159, v219
	v_fmac_f32_e32 v190, v158, v215
	v_add_f32_e32 v181, v181, v190
	v_mul_f32_e32 v190, v161, v216
	v_fmac_f32_e32 v190, v160, v214
	v_add_f32_e32 v181, v190, v181
	v_add_f32_e32 v180, v180, v181
	v_mov_b32_e32 v229, v228
	s_nop 1
	v_permlane32_swap_b32 v228, v229
	s_waitcnt lgkmcnt(0)
	s_nop 1
	v_add_f32_dpp v180, v180, v180 quad_perm:[1,0,3,2] row_mask:0xf bank_mask:0xf
	s_waitcnt lgkmcnt(0)
	s_nop 1
	v_add_f32_dpp v180, v180, v180 quad_perm:[2,3,0,1] row_mask:0xf bank_mask:0xf
	s_waitcnt lgkmcnt(0)
	s_nop 1
	v_add_f32_dpp v180, v180, v180 row_half_mirror row_mask:0xf bank_mask:0xf
	s_waitcnt lgkmcnt(0)
	s_nop 1
	v_add_f32_dpp v180, v180, v180 row_mirror row_mask:0xf bank_mask:0xf
	v_mov_b32_e32 v181, v180
	s_nop 1
	v_permlane16_swap_b32 v180, v181
	s_waitcnt lgkmcnt(0)
	v_add_f32_e32 v190, v180, v181
	v_mov_b32_e32 v191, v190
	s_nop 1
	v_permlane32_swap_b32 v190, v191
	s_and_saveexec_b64 s[30:31], s[38:39]
	s_cbranch_execz .LBB0_145
; __device__ __forceinline__ void shiftw_phase(const Args& a, int layer, LAS unsigned char* lds, int tid, int gw, int ngw, int lane) {
;     ...
;             if (lane < 5) { float r = accv[0]; r = lane == 1 ? accv[1] : r; r = lane == 2 ? accv[2] : r; r = lane == 3 ? accv[3] : r; r = lane == 4 ? accv[4] : r;
;                 SW[((size_t)kind * 5 + lane) * SWLD + n] = r; }
	s_waitcnt lgkmcnt(0)
	v_add_f32_e32 v180, v190, v191
	v_add_f32_e32 v191, v224, v225
	v_add_f32_e32 v192, v222, v223
	v_add_f32_e32 v190, v226, v227
	v_cndmask_b32_e64 v191, v192, v191, s[40:41]
	v_add_f32_e32 v181, v228, v229
	v_cndmask_b32_e64 v190, v191, v190, s[42:43]
	v_cndmask_b32_e64 v181, v190, v181, s[44:45]
	v_cndmask_b32_e64 v180, v181, v180, s[46:47]
	global_store_dword v[182:183], v180, off
	s_branch .LBB0_145

; #define LAS __attribute__((address_space(3)))
; __device__ __forceinline__ void unpack8(const u32x4 w, float (&f)[8]) { f[0] = bflo(w.x); f[1] = bfhi(w.x); f[2] = bflo(w.y); f[3] = bfhi(w.y); f[4] = bflo(w.z); f[5] = bfhi(w.z); f[6] = bflo(w.w); f[7] = bfhi(w.w); }
; __device__ __forceinline__ float wave_sum(float v) {
; #pragma unroll
;     for (int o = 1; o < 64; o <<= 1) v += __shfl_xor(v, o);
;     return v;
; }
; __device__ __forceinline__ void shiftw_phase(const Args& a, int layer, LAS unsigned char* lds, int tid, int gw, int ngw, int lane) {
;     ...
;         for (int n = gw; n < N; n += ngw) {
;             const bf16_t* wr_ = Wt + (size_t)n * DM + lane * 8;
;             float w[4][8];
; #pragma unroll
;             for (int j = 0; j < 4; ++j) unpack8(*(const u32x4*)(wr_ + 512 * j), w[j]);
;             float accv[5];
; #pragma unroll
;             for (int v = 0; v < 5; ++v) { float s_ = 0.f;
; #pragma unroll
;                 for (int j = 0; j < 4; ++j) { const LAS f32x4* sp = (const LAS f32x4*)(sh + v * DM + lane * 8 + 512 * j); const f32x4 s0 = sp[0], s1 = sp[1];
;                     s_ += (w[j][0] * s0[0] + w[j][1] * s0[1]) + (w[j][2] * s0[2] + w[j][3] * s0[3]) + (w[j][4] * s1[0] + w[j][5] * s1[1]) + (w[j][6] * s1[2] + w[j][7] * s1[3]); }
;                 accv[v] = wave_sum(s_); }
;             if (lane < 5) { float r = accv[0]; r = lane == 1 ? accv[1] : r; r = lane == 2 ? accv[2] : r; r = lane == 3 ? accv[3] : r; r = lane == 4 ? accv[4] : r;
;                 SW[((size_t)kind * 5 + lane) * SWLD + n] = r; }
.LBB0_1262:
	global_load_dwordx4 v[196:199], v[168:169], off offset:-2048
	global_load_dwordx4 v[204:207], v[168:169], off offset:-1024
	global_load_dwordx4 v[212:215], v[168:169], off
	global_load_dwordx4 v[220:223], v[168:169], off offset:1024
	s_waitcnt vmcnt(3)
	v_and_b32_e32 v195, 0xffff0000, v196
	v_and_b32_e32 v194, 0xffff0000, v197
	v_lshlrev_b32_e32 v192, 16, v196
	v_lshlrev_b32_e32 v191, 16, v197
	s_waitcnt lgkmcnt(0)
	v_mul_f32_e32 v180, v3, v195
	v_mul_f32_e32 v181, v5, v194
	v_and_b32_e32 v193, 0xffff0000, v198
	v_fmac_f32_e32 v180, v2, v192
	v_fmac_f32_e32 v181, v4, v191
	s_waitcnt lgkmcnt(0)
	v_lshlrev_b32_e32 v189, 16, v198
	v_add_f32_e32 v180, v180, v181
	v_mul_f32_e32 v181, v7, v193
	v_and_b32_e32 v190, 0xffff0000, v199
	v_fmac_f32_e32 v181, v6, v189
	v_lshlrev_b32_e32 v188, 16, v199
	v_add_f32_e32 v180, v180, v181
	v_mul_f32_e32 v181, v9, v190
	s_waitcnt vmcnt(2)
	v_and_b32_e32 v203, 0xffff0000, v204
	v_and_b32_e32 v202, 0xffff0000, v205
	v_fmac_f32_e32 v181, v8, v188
	v_lshlrev_b32_e32 v200, 16, v204
	v_lshlrev_b32_e32 v199, 16, v205
	s_waitcnt vmcnt(0)
	v_lshlrev_b32_e32 v216, 16, v220
	v_and_b32_e32 v219, 0xffff0000, v220
	v_add_f32_e32 v180, v181, v180
	v_mul_f32_e32 v181, v11, v203
	v_mul_f32_e32 v220, v13, v202
	v_and_b32_e32 v201, 0xffff0000, v206
	v_fmac_f32_e32 v181, v10, v200
	v_fmac_f32_e32 v220, v12, v199
	v_lshlrev_b32_e32 v197, 16, v206
	v_add_f32_e32 v181, v181, v220
	v_mul_f32_e32 v220, v15, v201
	v_and_b32_e32 v198, 0xffff0000, v207
	v_fmac_f32_e32 v220, v14, v197
	v_lshlrev_b32_e32 v196, 16, v207
	v_add_f32_e32 v181, v181, v220
	v_mul_f32_e32 v220, v17, v198
	v_fmac_f32_e32 v220, v16, v196
	v_and_b32_e32 v211, 0xffff0000, v212
	v_and_b32_e32 v210, 0xffff0000, v213
	v_add_f32_e32 v180, 0, v180
	v_add_f32_e32 v181, v220, v181
	v_lshlrev_b32_e32 v208, 16, v212
	v_lshlrev_b32_e32 v207, 16, v213
	v_add_f32_e32 v180, v180, v181
	v_mul_f32_e32 v181, v19, v211
	v_mul_f32_e32 v220, v21, v210
	v_and_b32_e32 v209, 0xffff0000, v214
	v_fmac_f32_e32 v181, v18, v208
	v_fmac_f32_e32 v220, v20, v207
	v_lshlrev_b32_e32 v205, 16, v214
	v_add_f32_e32 v181, v181, v220
	v_mul_f32_e32 v220, v23, v209
	v_and_b32_e32 v206, 0xffff0000, v215
	v_fmac_f32_e32 v220, v22, v205
	v_lshlrev_b32_e32 v204, 16, v215
	v_add_f32_e32 v181, v181, v220
	v_mul_f32_e32 v220, v25, v206
	v_fmac_f32_e32 v220, v24, v204
	v_and_b32_e32 v218, 0xffff0000, v221
	v_add_f32_e32 v181, v220, v181
	v_lshlrev_b32_e32 v215, 16, v221
	v_add_f32_e32 v180, v180, v181
	v_mul_f32_e32 v181, v27, v219
	v_mul_f32_e32 v220, v29, v218
	v_and_b32_e32 v217, 0xffff0000, v222
	v_fmac_f32_e32 v181, v26, v216
	v_fmac_f32_e32 v220, v28, v215
	v_lshlrev_b32_e32 v213, 16, v222
	v_add_f32_e32 v181, v181, v220
	v_mul_f32_e32 v220, v31, v217
	v_and_b32_e32 v214, 0xffff0000, v223
	v_fmac_f32_e32 v220, v30, v213
	v_lshlrev_b32_e32 v212, 16, v223
	v_add_f32_e32 v181, v181, v220
	v_mul_f32_e32 v220, v33, v214
	v_fmac_f32_e32 v220, v32, v212
	v_add_f32_e32 v181, v220, v181
	v_add_f32_e32 v180, v180, v181
	v_mul_f32_e32 v222, v45, v202
	v_fmac_f32_e32 v222, v44, v199
	v_mul_f32_e32 v224, v77, v202
	v_fmac_f32_e32 v224, v76, v199
	s_waitcnt lgkmcnt(0)
	s_nop 1
	v_add_f32_dpp v180, v180, v180 quad_perm:[1,0,3,2] row_mask:0xf bank_mask:0xf
	v_mul_f32_e32 v226, v109, v202
	v_fmac_f32_e32 v226, v108, v199
	s_waitcnt lgkmcnt(0)
	s_nop 1
	v_add_f32_dpp v180, v180, v180 quad_perm:[2,3,0,1] row_mask:0xf bank_mask:0xf
	s_waitcnt lgkmcnt(0)
	s_nop 1
	v_add_f32_dpp v180, v180, v180 row_half_mirror row_mask:0xf bank_mask:0xf
	s_waitcnt lgkmcnt(0)
	s_nop 1
	v_add_f32_dpp v180, v180, v180 row_mirror row_mask:0xf bank_mask:0xf
	v_mov_b32_e32 v181, v180
	s_nop 1
	v_permlane16_swap_b32 v180, v181
	s_waitcnt lgkmcnt(0)
	v_add_f32_e32 v220, v180, v181
	v_mul_f32_e32 v180, v35, v195
	v_mul_f32_e32 v181, v37, v194
	v_fmac_f32_e32 v180, v34, v192
	v_fmac_f32_e32 v181, v36, v191
	v_add_f32_e32 v180, v180, v181
	v_mul_f32_e32 v181, v39, v193
	v_fmac_f32_e32 v181, v38, v189
	v_add_f32_e32 v180, v180, v181
	v_mul_f32_e32 v181, v41, v190
	v_fmac_f32_e32 v181, v40, v188
	v_add_f32_e32 v180, v181, v180
	v_mul_f32_e32 v181, v43, v203
	v_fmac_f32_e32 v181, v42, v200
	v_add_f32_e32 v181, v181, v222
	v_mul_f32_e32 v222, v47, v201
	v_fmac_f32_e32 v222, v46, v197
	v_add_f32_e32 v181, v181, v222
	v_mul_f32_e32 v222, v49, v198
	v_fmac_f32_e32 v222, v48, v196
	v_add_f32_e32 v180, 0, v180
	v_add_f32_e32 v181, v222, v181
	v_add_f32_e32 v180, v180, v181
	v_mul_f32_e32 v181, v51, v211
	v_mul_f32_e32 v222, v53, v210
	v_fmac_f32_e32 v181, v50, v208
	v_fmac_f32_e32 v222, v52, v207
	v_add_f32_e32 v181, v181, v222
	v_mul_f32_e32 v222, v55, v209
	v_fmac_f32_e32 v222, v54, v205
	v_add_f32_e32 v181, v181, v222
	v_mul_f32_e32 v222, v57, v206
	v_fmac_f32_e32 v222, v56, v204
	v_add_f32_e32 v181, v222, v181
	v_add_f32_e32 v180, v180, v181
	v_mul_f32_e32 v181, v59, v219
	v_mul_f32_e32 v222, v61, v218
	v_fmac_f32_e32 v181, v58, v216
	v_fmac_f32_e32 v222, v60, v215
	v_add_f32_e32 v181, v181, v222
	v_mul_f32_e32 v222, v63, v217
	v_fmac_f32_e32 v222, v62, v213
	v_add_f32_e32 v181, v181, v222
	v_mul_f32_e32 v222, v65, v214
	v_fmac_f32_e32 v222, v64, v212
	v_add_f32_e32 v181, v222, v181
	v_add_f32_e32 v180, v180, v181
	v_mov_b32_e32 v221, v220
	s_nop 1
	v_permlane32_swap_b32 v220, v221
	s_waitcnt lgkmcnt(0)
	s_nop 1
	v_add_f32_dpp v180, v180, v180 quad_perm:[1,0,3,2] row_mask:0xf bank_mask:0xf
	s_waitcnt lgkmcnt(0)
	s_nop 1
	v_add_f32_dpp v180, v180, v180 quad_perm:[2,3,0,1] row_mask:0xf bank_mask:0xf
	s_waitcnt lgkmcnt(0)
	s_nop 1
	v_add_f32_dpp v180, v180, v180 row_half_mirror row_mask:0xf bank_mask:0xf
	s_waitcnt lgkmcnt(0)
; #define LAS __attribute__((address_space(3)))
; __device__ __forceinline__ void unpack8(const u32x4 w, float (&f)[8]) { f[0] = bflo(w.x); f[1] = bfhi(w.x); f[2] = bflo(w.y); f[3] = bfhi(w.y); f[4] = bflo(w.z); f[5] = bfhi(w.z); f[6] = bflo(w.w); f[7] = bfhi(w.w); }
; __device__ __forceinline__ float wave_sum(float v) {
; #pragma unroll
;     for (int o = 1; o < 64; o <<= 1) v += __shfl_xor(v, o);
;     return v;
; }
; __device__ __forceinline__ void shiftw_phase(const Args& a, int layer, LAS unsigned char* lds, int tid, int gw, int ngw, int lane) {
;     ...
;         for (int n = gw; n < N; n += ngw) {
;             const bf16_t* wr_ = Wt + (size_t)n * DM + lane * 8;
;             float w[4][8];
; #pragma unroll
;             for (int j = 0; j < 4; ++j) unpack8(*(const u32x4*)(wr_ + 512 * j), w[j]);
;             float accv[5];
; #pragma unroll
;             for (int v = 0; v < 5; ++v) { float s_ = 0.f;
; #pragma unroll
;                 for (int j = 0; j < 4; ++j) { const LAS f32x4* sp = (const LAS f32x4*)(sh + v * DM + lane * 8 + 512 * j); const f32x4 s0 = sp[0], s1 = sp[1];
;                     s_ += (w[j][0] * s0[0] + w[j][1] * s0[1]) + (w[j][2] * s0[2] + w[j][3] * s0[3]) + (w[j][4] * s1[0] + w[j][5] * s1[1]) + (w[j][6] * s1[2] + w[j][7] * s1[3]); }
;                 accv[v] = wave_sum(s_); }
;             if (lane < 5) { float r = accv[0]; r = lane == 1 ? accv[1] : r; r = lane == 2 ? accv[2] : r; r = lane == 3 ? accv[3] : r; r = lane == 4 ? accv[4] : r;
;                 SW[((size_t)kind * 5 + lane) * SWLD + n] = r; }
	s_nop 1
	v_add_f32_dpp v180, v180, v180 row_mirror row_mask:0xf bank_mask:0xf
	v_mov_b32_e32 v181, v180
	s_nop 1
	v_permlane16_swap_b32 v180, v181
	s_waitcnt lgkmcnt(0)
	v_add_f32_e32 v222, v180, v181
	v_mul_f32_e32 v180, v67, v195
	v_mul_f32_e32 v181, v69, v194
	v_fmac_f32_e32 v180, v66, v192
	v_fmac_f32_e32 v181, v68, v191
	v_add_f32_e32 v180, v180, v181
	v_mul_f32_e32 v181, v71, v193
	v_fmac_f32_e32 v181, v70, v189
	v_add_f32_e32 v180, v180, v181
	v_mul_f32_e32 v181, v73, v190
	v_fmac_f32_e32 v181, v72, v188
	v_add_f32_e32 v180, v181, v180
	v_mul_f32_e32 v181, v75, v203
	v_fmac_f32_e32 v181, v74, v200
	v_add_f32_e32 v181, v181, v224
	v_mul_f32_e32 v224, v79, v201
	v_fmac_f32_e32 v224, v78, v197
	v_add_f32_e32 v181, v181, v224
	v_mul_f32_e32 v224, v81, v198
	v_fmac_f32_e32 v224, v80, v196
	v_add_f32_e32 v180, 0, v180
	v_add_f32_e32 v181, v224, v181
	v_add_f32_e32 v180, v180, v181
	v_mul_f32_e32 v181, v83, v211
	v_mul_f32_e32 v224, v85, v210
	v_fmac_f32_e32 v181, v82, v208
	v_fmac_f32_e32 v224, v84, v207
	v_add_f32_e32 v181, v181, v224
	v_mul_f32_e32 v224, v87, v209
	v_fmac_f32_e32 v224, v86, v205
	v_add_f32_e32 v181, v181, v224
	v_mul_f32_e32 v224, v89, v206
	v_fmac_f32_e32 v224, v88, v204
	v_add_f32_e32 v181, v224, v181
	v_add_f32_e32 v180, v180, v181
	v_mul_f32_e32 v181, v91, v219
	v_mul_f32_e32 v224, v93, v218
	v_fmac_f32_e32 v181, v90, v216
	v_fmac_f32_e32 v224, v92, v215
	v_add_f32_e32 v181, v181, v224
	v_mul_f32_e32 v224, v95, v217
	v_fmac_f32_e32 v224, v94, v213
	v_add_f32_e32 v181, v181, v224
	v_mul_f32_e32 v224, v97, v214
	v_fmac_f32_e32 v224, v96, v212
	v_add_f32_e32 v181, v224, v181
	v_add_f32_e32 v180, v180, v181
	v_mov_b32_e32 v223, v222
	s_nop 1
	v_permlane32_swap_b32 v222, v223
	s_waitcnt lgkmcnt(0)
	s_nop 1
	v_add_f32_dpp v180, v180, v180 quad_perm:[1,0,3,2] row_mask:0xf bank_mask:0xf
	s_waitcnt lgkmcnt(0)
	s_nop 1
	v_add_f32_dpp v180, v180, v180 quad_perm:[2,3,0,1] row_mask:0xf bank_mask:0xf
	s_waitcnt lgkmcnt(0)
	s_nop 1
	v_add_f32_dpp v180, v180, v180 row_half_mirror row_mask:0xf bank_mask:0xf
	s_waitcnt lgkmcnt(0)
	s_nop 1
	v_add_f32_dpp v180, v180, v180 row_mirror row_mask:0xf bank_mask:0xf
	v_mov_b32_e32 v181, v180
	s_nop 1
	v_permlane16_swap_b32 v180, v181
	s_waitcnt lgkmcnt(0)
	v_add_f32_e32 v224, v180, v181
	v_mul_f32_e32 v180, v99, v195
	v_mul_f32_e32 v181, v101, v194
	v_fmac_f32_e32 v180, v98, v192
	v_fmac_f32_e32 v181, v100, v191
	v_add_f32_e32 v180, v180, v181
	v_mul_f32_e32 v181, v103, v193
	v_fmac_f32_e32 v181, v102, v189
	v_add_f32_e32 v180, v180, v181
	v_mul_f32_e32 v181, v105, v190
	v_fmac_f32_e32 v181, v104, v188
	v_add_f32_e32 v180, v181, v180
	v_mul_f32_e32 v181, v107, v203
	v_fmac_f32_e32 v181, v106, v200
	v_add_f32_e32 v181, v181, v226
	v_mul_f32_e32 v226, v111, v201
	v_fmac_f32_e32 v226, v110, v197
	v_add_f32_e32 v181, v181, v226
	v_mul_f32_e32 v226, v113, v198
	v_fmac_f32_e32 v226, v112, v196
	v_add_f32_e32 v180, 0, v180
	v_add_f32_e32 v181, v226, v181
	v_add_f32_e32 v180, v180, v181
	v_mul_f32_e32 v181, v115, v211
	v_mul_f32_e32 v226, v117, v210
	v_fmac_f32_e32 v181, v114, v208
	v_fmac_f32_e32 v226, v116, v207
	v_add_f32_e32 v181, v181, v226
	v_mul_f32_e32 v226, v119, v209
	v_fmac_f32_e32 v226, v118, v205
	v_add_f32_e32 v181, v181, v226
	v_mul_f32_e32 v226, v121, v206
	v_fmac_f32_e32 v226, v120, v204
	v_add_f32_e32 v181, v226, v181
	v_add_f32_e32 v180, v180, v181
	v_mul_f32_e32 v181, v123, v219
	v_mul_f32_e32 v226, v125, v218
	v_fmac_f32_e32 v181, v122, v216
	v_fmac_f32_e32 v226, v124, v215
	v_add_f32_e32 v181, v181, v226
	v_mul_f32_e32 v226, v127, v217
	v_fmac_f32_e32 v226, v126, v213
	v_add_f32_e32 v181, v181, v226
	v_mul_f32_e32 v226, v129, v214
	v_fmac_f32_e32 v226, v128, v212
	v_add_f32_e32 v181, v226, v181
	v_add_f32_e32 v180, v180, v181
	v_mov_b32_e32 v225, v224
	s_nop 1
	v_permlane32_swap_b32 v224, v225
	s_waitcnt lgkmcnt(0)
	s_nop 1
	v_add_f32_dpp v180, v180, v180 quad_perm:[1,0,3,2] row_mask:0xf bank_mask:0xf
	s_waitcnt lgkmcnt(0)
	s_nop 1
	v_add_f32_dpp v180, v180, v180 quad_perm:[2,3,0,1] row_mask:0xf bank_mask:0xf
	s_waitcnt lgkmcnt(0)
	s_nop 1
	v_add_f32_dpp v180, v180, v180 row_half_mirror row_mask:0xf bank_mask:0xf
	s_waitcnt lgkmcnt(0)
	s_nop 1
	v_add_f32_dpp v180, v180, v180 row_mirror row_mask:0xf bank_mask:0xf
	v_mov_b32_e32 v181, v180
	s_nop 1
	v_permlane16_swap_b32 v180, v181
	s_waitcnt lgkmcnt(0)
	v_add_f32_e32 v226, v180, v181
	v_mul_f32_e32 v180, v131, v195
	v_mul_f32_e32 v181, v133, v194
	v_fmac_f32_e32 v180, v130, v192
	v_fmac_f32_e32 v181, v132, v191
	v_add_f32_e32 v180, v180, v181
	v_mul_f32_e32 v181, v135, v193
	v_fmac_f32_e32 v181, v134, v189
	v_add_f32_e32 v180, v180, v181
	v_mul_f32_e32 v181, v137, v190
	v_fmac_f32_e32 v181, v136, v188
	v_add_f32_e32 v180, v181, v180
	v_mul_f32_e32 v181, v139, v203
	v_mul_f32_e32 v188, v141, v202
	v_fmac_f32_e32 v181, v138, v200
	v_fmac_f32_e32 v188, v140, v199
	v_add_f32_e32 v181, v181, v188
	v_mul_f32_e32 v188, v143, v201
	v_fmac_f32_e32 v188, v142, v197
	v_add_f32_e32 v181, v181, v188
	v_mul_f32_e32 v188, v145, v198
	v_fmac_f32_e32 v188, v144, v196
	v_add_f32_e32 v180, 0, v180
	v_add_f32_e32 v181, v188, v181
	v_add_f32_e32 v180, v180, v181
	v_mul_f32_e32 v181, v147, v211
	v_mul_f32_e32 v188, v149, v210
	v_fmac_f32_e32 v181, v146, v208
	v_fmac_f32_e32 v188, v148, v207
	v_add_f32_e32 v181, v181, v188
	v_mul_f32_e32 v188, v151, v209
	v_fmac_f32_e32 v188, v150, v205
	v_add_f32_e32 v181, v181, v188
	v_mul_f32_e32 v188, v153, v206
	v_fmac_f32_e32 v188, v152, v204
	v_add_f32_e32 v181, v188, v181
	v_add_f32_e32 v180, v180, v181
	v_mul_f32_e32 v181, v155, v219
	v_mul_f32_e32 v188, v157, v218
	v_fmac_f32_e32 v181, v154, v216
	v_fmac_f32_e32 v188, v156, v215
	v_add_f32_e32 v181, v181, v188
	v_mul_f32_e32 v188, v159, v217
	v_fmac_f32_e32 v188, v158, v213
	v_add_f32_e32 v181, v181, v188
	v_mul_f32_e32 v188, v161, v214
	v_fmac_f32_e32 v188, v160, v212
	v_add_f32_e32 v181, v188, v181
	v_add_f32_e32 v180, v180, v181
	v_mov_b32_e32 v227, v226
	s_nop 1
	v_permlane32_swap_b32 v226, v227
	s_waitcnt lgkmcnt(0)
	s_nop 1
	v_add_f32_dpp v180, v180, v180 quad_perm:[1,0,3,2] row_mask:0xf bank_mask:0xf
	s_waitcnt lgkmcnt(0)
	s_nop 1
	v_add_f32_dpp v180, v180, v180 quad_perm:[2,3,0,1] row_mask:0xf bank_mask:0xf
	s_waitcnt lgkmcnt(0)
	s_nop 1
	v_add_f32_dpp v180, v180, v180 row_half_mirror row_mask:0xf bank_mask:0xf
	s_waitcnt lgkmcnt(0)
	s_nop 1
	v_add_f32_dpp v180, v180, v180 row_mirror row_mask:0xf bank_mask:0xf
	v_mov_b32_e32 v181, v180
	s_nop 1
	v_permlane16_swap_b32 v180, v181
	s_waitcnt lgkmcnt(0)
	v_add_f32_e32 v188, v180, v181
	v_mov_b32_e32 v189, v188
	s_nop 1
	v_permlane32_swap_b32 v188, v189
	s_and_saveexec_b64 s[30:31], s[38:39]
	s_cbranch_execz .LBB0_1261
; __device__ __forceinline__ void shiftw_phase(const Args& a, int layer, LAS unsigned char* lds, int tid, int gw, int ngw, int lane) {
;     ...
;                 accv[v] = wave_sum(s_); }
;             if (lane < 5) { float r = accv[0]; r = lane == 1 ? accv[1] : r; r = lane == 2 ? accv[2] : r; r = lane == 3 ? accv[3] : r; r = lane == 4 ? accv[4] : r;
;                 SW[((size_t)kind * 5 + lane) * SWLD + n] = r; }
	s_waitcnt lgkmcnt(0)
	v_add_f32_e32 v180, v188, v189
	v_add_f32_e32 v189, v222, v223
	v_add_f32_e32 v190, v220, v221
	v_add_f32_e32 v188, v224, v225
	v_cndmask_b32_e64 v189, v190, v189, s[40:41]
	v_add_f32_e32 v181, v226, v227
	v_cndmask_b32_e64 v188, v189, v188, s[42:43]
	v_cndmask_b32_e64 v181, v188, v181, s[44:45]
	v_cndmask_b32_e64 v180, v181, v180, s[46:47]
	global_store_dword v[170:171], v180, off
	s_branch .LBB0_1261

; #define LAS __attribute__((address_space(3)))
; __device__ __forceinline__ void unpack8(const u32x4 w, float (&f)[8]) { f[0] = bflo(w.x); f[1] = bfhi(w.x); f[2] = bflo(w.y); f[3] = bfhi(w.y); f[4] = bflo(w.z); f[5] = bfhi(w.z); f[6] = bflo(w.w); f[7] = bfhi(w.w); }
; __device__ __forceinline__ float wave_sum(float v) {
; #pragma unroll
;     for (int o = 1; o < 64; o <<= 1) v += __shfl_xor(v, o);
;     return v;
; __device__ __forceinline__ void shiftw_phase(const Args& a, int layer, LAS unsigned char* lds, int tid, int gw, int ngw, int lane) {
;     ...
;             const bf16_t* wr_ = Wt + (size_t)n * DM + lane * 8;
;             float w[4][8];
; #pragma unroll
;             for (int j = 0; j < 4; ++j) unpack8(*(const u32x4*)(wr_ + 512 * j), w[j]);
;             float accv[5];
; #pragma unroll
;             for (int v = 0; v < 5; ++v) { float s_ = 0.f;
; #pragma unroll
;                 for (int j = 0; j < 4; ++j) { const LAS f32x4* sp = (const LAS f32x4*)(sh + v * DM + lane * 8 + 512 * j); const f32x4 s0 = sp[0], s1 = sp[1];
;                     s_ += (w[j][0] * s0[0] + w[j][1] * s0[1]) + (w[j][2] * s0[2] + w[j][3] * s0[3]) + (w[j][4] * s1[0] + w[j][5] * s1[1]) + (w[j][6] * s1[2] + w[j][7] * s1[3]); }
;                 accv[v] = wave_sum(s_); }
.LBB0_1309:
	global_load_dwordx4 v[194:197], v[168:169], off offset:-2048
	global_load_dwordx4 v[202:205], v[168:169], off offset:-1024
	global_load_dwordx4 v[210:213], v[168:169], off
	global_load_dwordx4 v[218:221], v[168:169], off offset:1024
	s_waitcnt vmcnt(3)
	v_lshlrev_b32_e32 v191, 16, v194
	v_and_b32_e32 v194, 0xffff0000, v194
	v_and_b32_e32 v193, 0xffff0000, v195
	v_lshlrev_b32_e32 v190, 16, v195
	s_waitcnt lgkmcnt(0)
	v_mul_f32_e32 v180, v3, v194
	v_mul_f32_e32 v181, v5, v193
	v_and_b32_e32 v192, 0xffff0000, v196
	v_fmac_f32_e32 v180, v2, v191
	v_fmac_f32_e32 v181, v4, v190
	s_waitcnt lgkmcnt(0)
	v_lshlrev_b32_e32 v188, 16, v196
	v_add_f32_e32 v180, v180, v181
	v_mul_f32_e32 v181, v7, v192
	v_and_b32_e32 v189, 0xffff0000, v197
	v_fmac_f32_e32 v181, v6, v188
	v_lshlrev_b32_e32 v187, 16, v197
	v_add_f32_e32 v180, v180, v181
	v_mul_f32_e32 v181, v9, v189
	s_waitcnt vmcnt(2)
	v_lshlrev_b32_e32 v199, 16, v202
	v_and_b32_e32 v202, 0xffff0000, v202
	v_and_b32_e32 v201, 0xffff0000, v203
	v_fmac_f32_e32 v181, v8, v187
	v_lshlrev_b32_e32 v198, 16, v203
	s_waitcnt vmcnt(0)
	v_lshlrev_b32_e32 v214, 16, v219
	v_and_b32_e32 v217, 0xffff0000, v219
	v_add_f32_e32 v180, v181, v180
	v_mul_f32_e32 v181, v11, v202
	v_mul_f32_e32 v219, v13, v201
	v_and_b32_e32 v200, 0xffff0000, v204
	v_fmac_f32_e32 v181, v10, v199
	v_fmac_f32_e32 v219, v12, v198
	v_lshlrev_b32_e32 v196, 16, v204
	v_add_f32_e32 v181, v181, v219
	v_mul_f32_e32 v219, v15, v200
	v_and_b32_e32 v197, 0xffff0000, v205
	v_fmac_f32_e32 v219, v14, v196
	v_lshlrev_b32_e32 v195, 16, v205
	v_add_f32_e32 v181, v181, v219
	v_mul_f32_e32 v219, v17, v197
	v_fmac_f32_e32 v219, v16, v195
	v_lshlrev_b32_e32 v207, 16, v210
	v_and_b32_e32 v210, 0xffff0000, v210
	v_and_b32_e32 v209, 0xffff0000, v211
	v_add_f32_e32 v180, 0, v180
	v_add_f32_e32 v181, v219, v181
	v_lshlrev_b32_e32 v206, 16, v211
	v_add_f32_e32 v180, v180, v181
	v_mul_f32_e32 v181, v19, v210
	v_mul_f32_e32 v219, v21, v209
	v_and_b32_e32 v208, 0xffff0000, v212
	v_fmac_f32_e32 v181, v18, v207
	v_fmac_f32_e32 v219, v20, v206
	v_lshlrev_b32_e32 v204, 16, v212
	v_add_f32_e32 v181, v181, v219
	v_mul_f32_e32 v219, v23, v208
	v_and_b32_e32 v205, 0xffff0000, v213
	v_fmac_f32_e32 v219, v22, v204
	v_lshlrev_b32_e32 v203, 16, v213
	v_add_f32_e32 v181, v181, v219
	v_mul_f32_e32 v219, v25, v205
	v_fmac_f32_e32 v219, v24, v203
	v_lshlrev_b32_e32 v215, 16, v218
	v_and_b32_e32 v218, 0xffff0000, v218
	v_add_f32_e32 v181, v219, v181
	v_add_f32_e32 v180, v180, v181
	v_mul_f32_e32 v181, v27, v218
	v_mul_f32_e32 v219, v29, v217
	v_and_b32_e32 v216, 0xffff0000, v220
	v_fmac_f32_e32 v181, v26, v215
	v_fmac_f32_e32 v219, v28, v214
	v_lshlrev_b32_e32 v212, 16, v220
	v_add_f32_e32 v181, v181, v219
	v_mul_f32_e32 v219, v31, v216
	v_and_b32_e32 v213, 0xffff0000, v221
	v_fmac_f32_e32 v219, v30, v212
	v_lshlrev_b32_e32 v211, 16, v221
	v_add_f32_e32 v181, v181, v219
	v_mul_f32_e32 v219, v33, v213
	v_fmac_f32_e32 v219, v32, v211
	v_add_f32_e32 v181, v219, v181
	v_add_f32_e32 v180, v180, v181
	v_mul_f32_e32 v221, v45, v201
	v_fmac_f32_e32 v221, v44, v198
	v_mul_f32_e32 v223, v77, v201
	v_fmac_f32_e32 v223, v76, v198
	s_waitcnt lgkmcnt(0)
	s_nop 1
	v_add_f32_dpp v180, v180, v180 quad_perm:[1,0,3,2] row_mask:0xf bank_mask:0xf
	v_mul_f32_e32 v225, v109, v201
	v_fmac_f32_e32 v225, v108, v198
	s_waitcnt lgkmcnt(0)
	s_nop 1
	v_add_f32_dpp v180, v180, v180 quad_perm:[2,3,0,1] row_mask:0xf bank_mask:0xf
	s_waitcnt lgkmcnt(0)
	s_nop 1
	v_add_f32_dpp v180, v180, v180 row_half_mirror row_mask:0xf bank_mask:0xf
	s_waitcnt lgkmcnt(0)
	s_nop 1
	v_add_f32_dpp v180, v180, v180 row_mirror row_mask:0xf bank_mask:0xf
	v_mov_b32_e32 v181, v180
	s_nop 1
	v_permlane16_swap_b32 v180, v181
	s_waitcnt lgkmcnt(0)
	v_add_f32_e32 v219, v180, v181
	v_mul_f32_e32 v180, v35, v194
	v_mul_f32_e32 v181, v37, v193
	v_fmac_f32_e32 v180, v34, v191
	v_fmac_f32_e32 v181, v36, v190
	v_add_f32_e32 v180, v180, v181
	v_mul_f32_e32 v181, v39, v192
	v_fmac_f32_e32 v181, v38, v188
	v_add_f32_e32 v180, v180, v181
	v_mul_f32_e32 v181, v41, v189
	v_fmac_f32_e32 v181, v40, v187
	v_add_f32_e32 v180, v181, v180
	v_mul_f32_e32 v181, v43, v202
	v_fmac_f32_e32 v181, v42, v199
	v_add_f32_e32 v181, v181, v221
	v_mul_f32_e32 v221, v47, v200
	v_fmac_f32_e32 v221, v46, v196
	v_add_f32_e32 v181, v181, v221
	v_mul_f32_e32 v221, v49, v197
	v_fmac_f32_e32 v221, v48, v195
	v_add_f32_e32 v180, 0, v180
	v_add_f32_e32 v181, v221, v181
	v_add_f32_e32 v180, v180, v181
	v_mul_f32_e32 v181, v51, v210
	v_mul_f32_e32 v221, v53, v209
	v_fmac_f32_e32 v181, v50, v207
	v_fmac_f32_e32 v221, v52, v206
	v_add_f32_e32 v181, v181, v221
	v_mul_f32_e32 v221, v55, v208
	v_fmac_f32_e32 v221, v54, v204
	v_add_f32_e32 v181, v181, v221
	v_mul_f32_e32 v221, v57, v205
	v_fmac_f32_e32 v221, v56, v203
	v_add_f32_e32 v181, v221, v181
	v_add_f32_e32 v180, v180, v181
	v_mul_f32_e32 v181, v59, v218
	v_mul_f32_e32 v221, v61, v217
	v_fmac_f32_e32 v181, v58, v215
	v_fmac_f32_e32 v221, v60, v214
	v_add_f32_e32 v181, v181, v221
	v_mul_f32_e32 v221, v63, v216
	v_fmac_f32_e32 v221, v62, v212
	v_add_f32_e32 v181, v181, v221
	v_mul_f32_e32 v221, v65, v213
	v_fmac_f32_e32 v221, v64, v211
	v_add_f32_e32 v181, v221, v181
	v_add_f32_e32 v180, v180, v181
	v_mov_b32_e32 v220, v219
	s_nop 1
	v_permlane32_swap_b32 v219, v220
	s_waitcnt lgkmcnt(0)
	s_nop 1
	v_add_f32_dpp v180, v180, v180 quad_perm:[1,0,3,2] row_mask:0xf bank_mask:0xf
	s_waitcnt lgkmcnt(0)
	s_nop 1
	v_add_f32_dpp v180, v180, v180 quad_perm:[2,3,0,1] row_mask:0xf bank_mask:0xf
	s_waitcnt lgkmcnt(0)
	s_nop 1
	v_add_f32_dpp v180, v180, v180 row_half_mirror row_mask:0xf bank_mask:0xf
	s_waitcnt lgkmcnt(0)
; #define LAS __attribute__((address_space(3)))
; __device__ __forceinline__ float wave_sum(float v) {
; #pragma unroll
;     for (int o = 1; o < 64; o <<= 1) v += __shfl_xor(v, o);
;     return v;
; __device__ __forceinline__ void shiftw_phase(const Args& a, int layer, LAS unsigned char* lds, int tid, int gw, int ngw, int lane) {
;     ...
;             for (int v = 0; v < 5; ++v) { float s_ = 0.f;
; #pragma unroll
;                 for (int j = 0; j < 4; ++j) { const LAS f32x4* sp = (const LAS f32x4*)(sh + v * DM + lane * 8 + 512 * j); const f32x4 s0 = sp[0], s1 = sp[1];
;                     s_ += (w[j][0] * s0[0] + w[j][1] * s0[1]) + (w[j][2] * s0[2] + w[j][3] * s0[3]) + (w[j][4] * s1[0] + w[j][5] * s1[1]) + (w[j][6] * s1[2] + w[j][7] * s1[3]); }
;                 accv[v] = wave_sum(s_); }
;             if (lane < 5) { float r = accv[0]; r = lane == 1 ? accv[1] : r; r = lane == 2 ? accv[2] : r; r = lane == 3 ? accv[3] : r; r = lane == 4 ? accv[4] : r;
	s_nop 1
	v_add_f32_dpp v180, v180, v180 row_mirror row_mask:0xf bank_mask:0xf
	v_mov_b32_e32 v181, v180
	s_nop 1
	v_permlane16_swap_b32 v180, v181
	s_waitcnt lgkmcnt(0)
	v_add_f32_e32 v221, v180, v181
	v_mul_f32_e32 v180, v67, v194
	v_mul_f32_e32 v181, v69, v193
	v_fmac_f32_e32 v180, v66, v191
	v_fmac_f32_e32 v181, v68, v190
	v_add_f32_e32 v180, v180, v181
	v_mul_f32_e32 v181, v71, v192
	v_fmac_f32_e32 v181, v70, v188
	v_add_f32_e32 v180, v180, v181
	v_mul_f32_e32 v181, v73, v189
	v_fmac_f32_e32 v181, v72, v187
	v_add_f32_e32 v180, v181, v180
	v_mul_f32_e32 v181, v75, v202
	v_fmac_f32_e32 v181, v74, v199
	v_add_f32_e32 v181, v181, v223
	v_mul_f32_e32 v223, v79, v200
	v_fmac_f32_e32 v223, v78, v196
	v_add_f32_e32 v181, v181, v223
	v_mul_f32_e32 v223, v81, v197
	v_fmac_f32_e32 v223, v80, v195
	v_add_f32_e32 v180, 0, v180
	v_add_f32_e32 v181, v223, v181
	v_add_f32_e32 v180, v180, v181
	v_mul_f32_e32 v181, v83, v210
	v_mul_f32_e32 v223, v85, v209
	v_fmac_f32_e32 v181, v82, v207
	v_fmac_f32_e32 v223, v84, v206
	v_add_f32_e32 v181, v181, v223
	v_mul_f32_e32 v223, v87, v208
	v_fmac_f32_e32 v223, v86, v204
	v_add_f32_e32 v181, v181, v223
	v_mul_f32_e32 v223, v89, v205
	v_fmac_f32_e32 v223, v88, v203
	v_add_f32_e32 v181, v223, v181
	v_add_f32_e32 v180, v180, v181
	v_mul_f32_e32 v181, v91, v218
	v_mul_f32_e32 v223, v93, v217
	v_fmac_f32_e32 v181, v90, v215
	v_fmac_f32_e32 v223, v92, v214
	v_add_f32_e32 v181, v181, v223
	v_mul_f32_e32 v223, v95, v216
	v_fmac_f32_e32 v223, v94, v212
	v_add_f32_e32 v181, v181, v223
	v_mul_f32_e32 v223, v97, v213
	v_fmac_f32_e32 v223, v96, v211
	v_add_f32_e32 v181, v223, v181
	v_add_f32_e32 v180, v180, v181
	v_mov_b32_e32 v222, v221
	s_nop 1
	v_permlane32_swap_b32 v221, v222
	s_waitcnt lgkmcnt(0)
	s_nop 1
	v_add_f32_dpp v180, v180, v180 quad_perm:[1,0,3,2] row_mask:0xf bank_mask:0xf
	s_waitcnt lgkmcnt(0)
	s_nop 1
	v_add_f32_dpp v180, v180, v180 quad_perm:[2,3,0,1] row_mask:0xf bank_mask:0xf
	s_waitcnt lgkmcnt(0)
	s_nop 1
	v_add_f32_dpp v180, v180, v180 row_half_mirror row_mask:0xf bank_mask:0xf
	s_waitcnt lgkmcnt(0)
	s_nop 1
	v_add_f32_dpp v180, v180, v180 row_mirror row_mask:0xf bank_mask:0xf
	v_mov_b32_e32 v181, v180
	s_nop 1
	v_permlane16_swap_b32 v180, v181
	s_waitcnt lgkmcnt(0)
	v_add_f32_e32 v223, v180, v181
	v_mul_f32_e32 v180, v99, v194
	v_mul_f32_e32 v181, v101, v193
	v_fmac_f32_e32 v180, v98, v191
	v_fmac_f32_e32 v181, v100, v190
	v_add_f32_e32 v180, v180, v181
	v_mul_f32_e32 v181, v103, v192
	v_fmac_f32_e32 v181, v102, v188
	v_add_f32_e32 v180, v180, v181
	v_mul_f32_e32 v181, v105, v189
	v_fmac_f32_e32 v181, v104, v187
	v_add_f32_e32 v180, v181, v180
	v_mul_f32_e32 v181, v107, v202
	v_fmac_f32_e32 v181, v106, v199
	v_add_f32_e32 v181, v181, v225
	v_mul_f32_e32 v225, v111, v200
	v_fmac_f32_e32 v225, v110, v196
	v_add_f32_e32 v181, v181, v225
	v_mul_f32_e32 v225, v113, v197
	v_fmac_f32_e32 v225, v112, v195
	v_add_f32_e32 v180, 0, v180
	v_add_f32_e32 v181, v225, v181
	v_add_f32_e32 v180, v180, v181
	v_mul_f32_e32 v181, v115, v210
	v_mul_f32_e32 v225, v117, v209
	v_fmac_f32_e32 v181, v114, v207
	v_fmac_f32_e32 v225, v116, v206
	v_add_f32_e32 v181, v181, v225
	v_mul_f32_e32 v225, v119, v208
	v_fmac_f32_e32 v225, v118, v204
	v_add_f32_e32 v181, v181, v225
	v_mul_f32_e32 v225, v121, v205
	v_fmac_f32_e32 v225, v120, v203
	v_add_f32_e32 v181, v225, v181
	v_add_f32_e32 v180, v180, v181
	v_mul_f32_e32 v181, v123, v218
	v_mul_f32_e32 v225, v125, v217
	v_fmac_f32_e32 v181, v122, v215
	v_fmac_f32_e32 v225, v124, v214
	v_add_f32_e32 v181, v181, v225
	v_mul_f32_e32 v225, v127, v216
	v_fmac_f32_e32 v225, v126, v212
	v_add_f32_e32 v181, v181, v225
	v_mul_f32_e32 v225, v129, v213
	v_fmac_f32_e32 v225, v128, v211
	v_add_f32_e32 v181, v225, v181
	v_add_f32_e32 v180, v180, v181
	v_mov_b32_e32 v224, v223
	s_nop 1
	v_permlane32_swap_b32 v223, v224
	s_waitcnt lgkmcnt(0)
	s_nop 1
	v_add_f32_dpp v180, v180, v180 quad_perm:[1,0,3,2] row_mask:0xf bank_mask:0xf
	s_waitcnt lgkmcnt(0)
	s_nop 1
	v_add_f32_dpp v180, v180, v180 quad_perm:[2,3,0,1] row_mask:0xf bank_mask:0xf
	s_waitcnt lgkmcnt(0)
	s_nop 1
	v_add_f32_dpp v180, v180, v180 row_half_mirror row_mask:0xf bank_mask:0xf
	s_waitcnt lgkmcnt(0)
	s_nop 1
	v_add_f32_dpp v180, v180, v180 row_mirror row_mask:0xf bank_mask:0xf
	v_mov_b32_e32 v181, v180
	s_nop 1
	v_permlane16_swap_b32 v180, v181
	s_waitcnt lgkmcnt(0)
	v_add_f32_e32 v225, v180, v181
	v_mul_f32_e32 v180, v131, v194
	v_mul_f32_e32 v181, v133, v193
	v_fmac_f32_e32 v180, v130, v191
	v_fmac_f32_e32 v181, v132, v190
	v_add_f32_e32 v180, v180, v181
	v_mul_f32_e32 v181, v135, v192
	v_fmac_f32_e32 v181, v134, v188
	v_add_f32_e32 v180, v180, v181
	v_mul_f32_e32 v181, v137, v189
	v_fmac_f32_e32 v181, v136, v187
	v_add_f32_e32 v180, v181, v180
	v_mul_f32_e32 v181, v139, v202
	v_mul_f32_e32 v187, v141, v201
	v_fmac_f32_e32 v181, v138, v199
	v_fmac_f32_e32 v187, v140, v198
	v_add_f32_e32 v181, v181, v187
	v_mul_f32_e32 v187, v143, v200
	v_fmac_f32_e32 v187, v142, v196
	v_add_f32_e32 v181, v181, v187
	v_mul_f32_e32 v187, v145, v197
	v_fmac_f32_e32 v187, v144, v195
	v_add_f32_e32 v180, 0, v180
	v_add_f32_e32 v181, v187, v181
	v_add_f32_e32 v180, v180, v181
	v_mul_f32_e32 v181, v147, v210
	v_mul_f32_e32 v187, v149, v209
	v_fmac_f32_e32 v181, v146, v207
	v_fmac_f32_e32 v187, v148, v206
	v_add_f32_e32 v181, v181, v187
	v_mul_f32_e32 v187, v151, v208
	v_fmac_f32_e32 v187, v150, v204
	v_add_f32_e32 v181, v181, v187
	v_mul_f32_e32 v187, v153, v205
	v_fmac_f32_e32 v187, v152, v203
	v_add_f32_e32 v181, v187, v181
	v_add_f32_e32 v180, v180, v181
	v_mul_f32_e32 v181, v155, v218
	v_mul_f32_e32 v187, v157, v217
	v_fmac_f32_e32 v181, v154, v215
	v_fmac_f32_e32 v187, v156, v214
	v_add_f32_e32 v181, v181, v187
	v_mul_f32_e32 v187, v159, v216
	v_fmac_f32_e32 v187, v158, v212
	v_add_f32_e32 v181, v181, v187
	v_mul_f32_e32 v187, v161, v213
	v_fmac_f32_e32 v187, v160, v211
	v_add_f32_e32 v181, v187, v181
	v_add_f32_e32 v180, v180, v181
	v_mov_b32_e32 v226, v225
	s_nop 1
	v_permlane32_swap_b32 v225, v226
	s_waitcnt lgkmcnt(0)
	s_nop 1
	v_add_f32_dpp v180, v180, v180 quad_perm:[1,0,3,2] row_mask:0xf bank_mask:0xf
	s_waitcnt lgkmcnt(0)
	s_nop 1
	v_add_f32_dpp v180, v180, v180 quad_perm:[2,3,0,1] row_mask:0xf bank_mask:0xf
	s_waitcnt lgkmcnt(0)
	s_nop 1
	v_add_f32_dpp v180, v180, v180 row_half_mirror row_mask:0xf bank_mask:0xf
	s_waitcnt lgkmcnt(0)
	s_nop 1
	v_add_f32_dpp v180, v180, v180 row_mirror row_mask:0xf bank_mask:0xf
	v_mov_b32_e32 v181, v180
	s_nop 1
	v_permlane16_swap_b32 v180, v181
	s_waitcnt lgkmcnt(0)
	v_add_f32_e32 v187, v180, v181
	v_mov_b32_e32 v188, v187
	s_nop 1
	v_permlane32_swap_b32 v187, v188
	s_and_saveexec_b64 s[30:31], s[38:39]
	s_cbranch_execz .LBB0_1308
; __device__ __forceinline__ void shiftw_phase(const Args& a, int layer, LAS unsigned char* lds, int tid, int gw, int ngw, int lane) {
;     ...
;                 accv[v] = wave_sum(s_); }
;             if (lane < 5) { float r = accv[0]; r = lane == 1 ? accv[1] : r; r = lane == 2 ? accv[2] : r; r = lane == 3 ? accv[3] : r; r = lane == 4 ? accv[4] : r;
;                 SW[((size_t)kind * 5 + lane) * SWLD + n] = r; }
	s_waitcnt lgkmcnt(0)
	v_add_f32_e32 v180, v187, v188
	v_add_f32_e32 v188, v221, v222
	v_add_f32_e32 v189, v219, v220
	v_add_f32_e32 v187, v223, v224
	v_cndmask_b32_e64 v188, v189, v188, s[40:41]
	v_add_f32_e32 v181, v225, v226
	v_cndmask_b32_e64 v187, v188, v187, s[42:43]
	v_cndmask_b32_e64 v181, v187, v181, s[44:45]
	v_cndmask_b32_e64 v180, v181, v180, s[46:47]
	global_store_dword v[170:171], v180, off
	s_branch .LBB0_1308
